# grid barrier trimmed: non-leader workgroups poll the cross-XCC generation word directly and issue their L1 invalidate before the poll loop (on top of v31)
# speedup vs baseline: 1.0110x; 1.0045x over previous
; __device__ __forceinline__ unsigned xb_ld(unsigned* p)              { return __hip_atomic_load(p, __ATOMIC_RELAXED, __HIP_MEMORY_SCOPE_AGENT); }
; __device__ __forceinline__ unsigned xb_add(unsigned* p, unsigned v) { return __hip_atomic_fetch_add(p, v, __ATOMIC_RELAXED, __HIP_MEMORY_SCOPE_AGENT); }
; #define XB_SPIN(cond, bar) do { unsigned _sp = 0; while (cond) { __builtin_amdgcn_s_sleep(1); \
;     if ((++_sp & 255u) == 0u) { if (xb_ld(&(bar)[XB_TMO])) break; if (_sp > XB_SPIN_CAP) { atomicAdd(&(bar)[XB_TMO], 1u); break; } } } } while (0)
; __device__ __forceinline__ void xcd_barrier(const XcdBarrier& b, int tid) {
;     ...
;         const unsigned old = xb_add(&bar[XB_XSUB(b.x)], 1u);
;         const unsigned gen = old / nloc;
;         if (old + 1u == (gen + 1u) * nloc) {
;             __builtin_amdgcn_fence(__ATOMIC_RELEASE, "agent");
;             asm volatile("s_waitcnt vmcnt(0)" ::: "memory");
;             const unsigned og = xb_add(&bar[XB_TOP], 1u);
;             const unsigned tg = og / nx;
;             if (og + 1u == (tg + 1u) * nx) xb_add(&bar[XB_TOPGEN], 1u);
;             else XB_SPIN(xb_ld(&bar[XB_TOPGEN]) == tg, bar);
;             __builtin_amdgcn_fence(__ATOMIC_ACQUIRE, "agent");
;             xb_add(&bar[XB_XGEN(b.x)], 1u);
;             asm volatile("s_waitcnt vmcnt(0)" ::: "memory");
;         } else {
;             XB_SPIN(xb_ld(&bar[XB_XGEN(b.x)]) == gen, bar);
;             __builtin_amdgcn_fence(__ATOMIC_ACQUIRE, "agent");
;             asm volatile("s_waitcnt vmcnt(0)" ::: "memory");
;         }
.LBB0_285:
	s_or_b64 exec, exec, s[2:3]
	v_cvt_f32_u32_e32 v4, v2
	s_waitcnt vmcnt(0)
	v_readfirstlane_b32 s2, v3
	v_sub_u32_e32 v3, 0, v2
	v_rcp_iflag_f32_e32 v4, v4
	v_add_u32_e32 v5, s2, v1
	v_mul_f32_e32 v4, 0x4f7ffffe, v4
	v_cvt_u32_f32_e32 v4, v4
	v_mul_lo_u32 v1, v3, v4
	v_mul_hi_u32 v1, v4, v1
	v_add_u32_e32 v1, v4, v1
	v_mul_hi_u32 v1, v5, v1
	v_mul_lo_u32 v3, v1, v2
	v_sub_u32_e32 v3, v5, v3
	v_add_u32_e32 v4, 1, v1
	v_cmp_ge_u32_e32 vcc, v3, v2
	s_nop 1
	v_cndmask_b32_e32 v1, v1, v4, vcc
	v_sub_u32_e32 v4, v3, v2
	v_cndmask_b32_e32 v3, v3, v4, vcc
	v_add_u32_e32 v4, 1, v1
	v_cmp_ge_u32_e32 vcc, v3, v2
	v_add_u32_e32 v3, 1, v5
	s_nop 0
	v_cndmask_b32_e32 v1, v1, v4, vcc
	v_mul_lo_u32 v4, v2, v1
	v_add_u32_e32 v2, v4, v2
	v_cmp_ne_u32_e32 vcc, v3, v2
	s_and_saveexec_b64 s[2:3], vcc
	s_xor_b64 s[2:3], exec, s[2:3]
	s_cbranch_execz .LBB0_316
	s_waitcnt lgkmcnt(0)
	buffer_inv sc1
	global_load_dword v0, v213, s[88:89] sc1
	s_waitcnt vmcnt(0)
	v_cmp_eq_u32_e32 vcc, v0, v1
	s_and_saveexec_b64 s[6:7], vcc
	s_cbranch_execz .LBB0_315
	s_mov_b32 s4, 1
	s_mov_b64 s[12:13], 0
	s_branch .LBB0_289

; __device__ __forceinline__ unsigned xb_ld(unsigned* p)              { return __hip_atomic_load(p, __ATOMIC_RELAXED, __HIP_MEMORY_SCOPE_AGENT); }
; __device__ __forceinline__ unsigned xb_add(unsigned* p, unsigned v) { return __hip_atomic_fetch_add(p, v, __ATOMIC_RELAXED, __HIP_MEMORY_SCOPE_AGENT); }
; #define XB_SPIN(cond, bar) do { unsigned _sp = 0; while (cond) { __builtin_amdgcn_s_sleep(1); \
;     if ((++_sp & 255u) == 0u) { if (xb_ld(&(bar)[XB_TMO])) break; if (_sp > XB_SPIN_CAP) { atomicAdd(&(bar)[XB_TMO], 1u); break; } } } } while (0)
; __device__ __forceinline__ void xcd_barrier(const XcdBarrier& b, int tid) {
;     ...
;             else XB_SPIN(xb_ld(&bar[XB_TOPGEN]) == tg, bar);
;             __builtin_amdgcn_fence(__ATOMIC_ACQUIRE, "agent");
;             xb_add(&bar[XB_XGEN(b.x)], 1u);
;             asm volatile("s_waitcnt vmcnt(0)" ::: "memory");
;         } else {
;             XB_SPIN(xb_ld(&bar[XB_XGEN(b.x)]) == gen, bar);
;             __builtin_amdgcn_fence(__ATOMIC_ACQUIRE, "agent");
.LBB0_291:
	global_load_dword v0, v213, s[88:89] sc1
	s_add_i32 s4, s4, 1
	s_mov_b64 s[24:25], -1
	s_waitcnt vmcnt(0)
	v_cmp_ne_u32_e32 vcc, v0, v1
	s_orn2_b64 s[18:19], vcc, exec
	s_branch .LBB0_288

; __device__ __forceinline__ unsigned xb_ld(unsigned* p)              { return __hip_atomic_load(p, __ATOMIC_RELAXED, __HIP_MEMORY_SCOPE_AGENT); }
; __device__ __forceinline__ unsigned xb_add(unsigned* p, unsigned v) { return __hip_atomic_fetch_add(p, v, __ATOMIC_RELAXED, __HIP_MEMORY_SCOPE_AGENT); }
; #define XB_SPIN(cond, bar) do { unsigned _sp = 0; while (cond) { __builtin_amdgcn_s_sleep(1); \
;     if ((++_sp & 255u) == 0u) { if (xb_ld(&(bar)[XB_TMO])) break; if (_sp > XB_SPIN_CAP) { atomicAdd(&(bar)[XB_TMO], 1u); break; } } } } while (0)
; __device__ __forceinline__ void xcd_barrier(const XcdBarrier& b, int tid) {
;     ...
;         const unsigned old = xb_add(&bar[XB_XSUB(b.x)], 1u);
;         const unsigned gen = old / nloc;
;         if (old + 1u == (gen + 1u) * nloc) {
;             __builtin_amdgcn_fence(__ATOMIC_RELEASE, "agent");
;             asm volatile("s_waitcnt vmcnt(0)" ::: "memory");
;             const unsigned og = xb_add(&bar[XB_TOP], 1u);
;             const unsigned tg = og / nx;
;             if (og + 1u == (tg + 1u) * nx) xb_add(&bar[XB_TOPGEN], 1u);
;             else XB_SPIN(xb_ld(&bar[XB_TOPGEN]) == tg, bar);
;             __builtin_amdgcn_fence(__ATOMIC_ACQUIRE, "agent");
;             xb_add(&bar[XB_XGEN(b.x)], 1u);
;             asm volatile("s_waitcnt vmcnt(0)" ::: "memory");
;         } else {
;             XB_SPIN(xb_ld(&bar[XB_XGEN(b.x)]) == gen, bar);
;             __builtin_amdgcn_fence(__ATOMIC_ACQUIRE, "agent");
;             asm volatile("s_waitcnt vmcnt(0)" ::: "memory");
;         }
.LBB0_302:
	s_or_b64 exec, exec, s[2:3]
	v_cvt_f32_u32_e32 v4, v2
	s_waitcnt vmcnt(0)
	v_readfirstlane_b32 s2, v3
	v_sub_u32_e32 v3, 0, v2
	v_rcp_iflag_f32_e32 v4, v4
	v_add_u32_e32 v5, s2, v1
	v_mul_f32_e32 v4, 0x4f7ffffe, v4
	v_cvt_u32_f32_e32 v4, v4
	v_mul_lo_u32 v1, v3, v4
	v_mul_hi_u32 v1, v4, v1
	v_add_u32_e32 v1, v4, v1
	v_mul_hi_u32 v1, v5, v1
	v_mul_lo_u32 v3, v1, v2
	v_sub_u32_e32 v3, v5, v3
	v_add_u32_e32 v4, 1, v1
	v_cmp_ge_u32_e32 vcc, v3, v2
	s_nop 1
	v_cndmask_b32_e32 v1, v1, v4, vcc
	v_sub_u32_e32 v4, v3, v2
	v_cndmask_b32_e32 v3, v3, v4, vcc
	v_add_u32_e32 v4, 1, v1
	v_cmp_ge_u32_e32 vcc, v3, v2
	v_add_u32_e32 v3, 1, v5
	s_nop 0
	v_cndmask_b32_e32 v1, v1, v4, vcc
	v_mul_lo_u32 v4, v2, v1
	v_add_u32_e32 v2, v4, v2
	v_cmp_ne_u32_e32 vcc, v3, v2
	s_and_saveexec_b64 s[2:3], vcc
	s_xor_b64 s[2:3], exec, s[2:3]
	s_cbranch_execz .LBB0_333
	s_waitcnt lgkmcnt(0)
	buffer_inv sc1
	global_load_dword v0, v213, s[88:89] sc1
	s_waitcnt vmcnt(0)
	v_cmp_eq_u32_e32 vcc, v0, v1
	s_and_saveexec_b64 s[6:7], vcc
	s_cbranch_execz .LBB0_332
	s_mov_b32 s5, 1
	s_mov_b64 s[12:13], 0
	s_branch .LBB0_306

; __device__ __forceinline__ unsigned xb_ld(unsigned* p)              { return __hip_atomic_load(p, __ATOMIC_RELAXED, __HIP_MEMORY_SCOPE_AGENT); }
; __device__ __forceinline__ unsigned xb_add(unsigned* p, unsigned v) { return __hip_atomic_fetch_add(p, v, __ATOMIC_RELAXED, __HIP_MEMORY_SCOPE_AGENT); }
; #define XB_SPIN(cond, bar) do { unsigned _sp = 0; while (cond) { __builtin_amdgcn_s_sleep(1); \
;     if ((++_sp & 255u) == 0u) { if (xb_ld(&(bar)[XB_TMO])) break; if (_sp > XB_SPIN_CAP) { atomicAdd(&(bar)[XB_TMO], 1u); break; } } } } while (0)
; __device__ __forceinline__ void xcd_barrier(const XcdBarrier& b, int tid) {
;     ...
;             else XB_SPIN(xb_ld(&bar[XB_TOPGEN]) == tg, bar);
;             __builtin_amdgcn_fence(__ATOMIC_ACQUIRE, "agent");
;             xb_add(&bar[XB_XGEN(b.x)], 1u);
;             asm volatile("s_waitcnt vmcnt(0)" ::: "memory");
;         } else {
;             XB_SPIN(xb_ld(&bar[XB_XGEN(b.x)]) == gen, bar);
;             __builtin_amdgcn_fence(__ATOMIC_ACQUIRE, "agent");
.LBB0_308:
	global_load_dword v0, v213, s[88:89] sc1
	s_add_i32 s5, s5, 1
	s_mov_b64 s[24:25], -1
	s_waitcnt vmcnt(0)
	v_cmp_ne_u32_e32 vcc, v0, v1
	s_orn2_b64 s[18:19], vcc, exec
	s_branch .LBB0_305

; __device__ __forceinline__ unsigned xb_ld(unsigned* p)              { return __hip_atomic_load(p, __ATOMIC_RELAXED, __HIP_MEMORY_SCOPE_AGENT); }
; #define XB_SPIN(cond, bar) do { unsigned _sp = 0; while (cond) { __builtin_amdgcn_s_sleep(1); \
;     if ((++_sp & 255u) == 0u) { if (xb_ld(&(bar)[XB_TMO])) break; if (_sp > XB_SPIN_CAP) { atomicAdd(&(bar)[XB_TMO], 1u); break; } } } } while (0)
; __device__ __forceinline__ void xcd_barrier(const XcdBarrier& b, int tid) {
;     ...
;             XB_SPIN(xb_ld(&bar[XB_XGEN(b.x)]) == gen, bar);
;             __builtin_amdgcn_fence(__ATOMIC_ACQUIRE, "agent");
;             asm volatile("s_waitcnt vmcnt(0)" ::: "memory");
;         }
.LBB0_315:
	s_or_b64 exec, exec, s[6:7]
	s_waitcnt vmcnt(0)
	s_waitcnt vmcnt(0)
